# attention unit queue: MLA+diff units interleaved and sorted by query block (heaviest first) so the queue tail is light
# baseline (speedup 1.0000x reference)
; __device__ __forceinline__ void attn_phase(LAS unsigned char* lds, int* counter, const bf16_t* __restrict__ P, const bf16_t* __restrict__ Qm, const bf16_t* __restrict__ Kmla, ...
;     ...
;         if (u < 128) { qb = 15 - ((u & 63) >> 2); r = 64 + bq * 8 + (u >> 6) * 4 + (u & 3); }
;         else if (u < 192) { const int v_ = u - 128; qb = 15 - ((v_ & 31) >> 1); r = 32 + bq * 4 + (v_ >> 5) * 2 + (v_ & 1); }
;         else { const int v_ = u - 192; qb = 15 - ((v_ & 31) >> 1); r = bq * 4 + (v_ >> 5) * 2 + (v_ & 1); }
;         const int t0 = qb * 256, tq = t0 + 32 * wid + r32;
.LBB0_674:
	s_or_b64 exec, exec, s[2:3]
	v_mov_b32_e32 v0, s57
	s_waitcnt lgkmcnt(0)
	s_barrier
	ds_read_b32 v0, v0
	s_mov_b64 s[2:3], -1
	s_waitcnt lgkmcnt(0)
	v_readfirstlane_b32 s4, v0
	s_cmpk_gt_i32 s4, 0xff
	s_cbranch_scc1 .LBB0_669
	s_cmpk_gt_i32 s4, 0x7f
	s_cbranch_scc0 .LBB0_681
	s_and_b32 s2, s4, 4
	s_cmp_lg_u32 s2, 0
	s_cselect_b32 s2, s37, s36
	s_and_b32 s3, s4, 3
	s_or_b32 s41, s2, s3
	s_lshr_b32 s5, s4, 3
	s_mov_b64 s[2:3], 0
